# scan: chunk-start state stores marked streaming (nt)
# speedup vs baseline: 1.0061x; 1.0061x over previous
; __device__ __forceinline__ float bf_lo(unsigned u) { return __uint_as_float(u << 16); }
; __device__ __forceinline__ float bf_hi(unsigned u) { return __uint_as_float(u & 0xffff0000u); }
; __device__ __forceinline__ unsigned pk2(float lo, float hi) { return pg8::cvt_pk_bf16(lo, hi); }
; #define SCAN_LOAD_D(slot, cc) { const int c_ = (cc) < NCH ? (cc) : NCH - 1; const bf16_t* bcn = bc0 + (size_t)c_ * 4096; \
;             _Pragma("unroll") for (int t = 0; t < 4; ++t) { cb[slot][t] = *(const u32x2*)(bcn + 256 * t); cm[slot][t] = mixer == 2 ? *(const f32x4*)(mv0 + (size_t)c_ * 64 + 16 * t) : (f32x4){g64, g64, g64, g64}; } }
; __device__ __forceinline__ void scan_phase(const Ctx& X, int wave, int lane) {
;     ...
;         SCAN_LOAD_D(0, 0) SCAN_LOAD_D(1, 1) SCAN_LOAD_D(2, 2)
; #pragma unroll 1
;         for (int c0 = 0; c0 < NCH; c0 += 4) {
; #pragma unroll
;             for (int k = 0; k < 4; ++k) {
;                 const int c = c0 + k;
;                 SCAN_LOAD_D((k + 3) & 3, c + 3)
;                 bf16_t* bcc = bc0 + (size_t)c * 4096;
; #pragma unroll
;                 for (int t = 0; t < 4; ++t) { u32x2 sp; sp.x = pk2(S[t][0], S[t][1]); sp.y = pk2(S[t][2], S[t][3]);
;                     asm volatile("" : "+v"(sp.x) : "v"(cb[k][t].x));
;                     *(u32x2*)(bcc + 256 * t) = sp;
;                     S[t][0] = cm[k][t].x * S[t][0] + bf_lo(cb[k][t].x); S[t][1] = cm[k][t].y * S[t][1] + bf_hi(cb[k][t].x);
;                     S[t][2] = cm[k][t].z * S[t][2] + bf_lo(cb[k][t].y); S[t][3] = cm[k][t].w * S[t][3] + bf_hi(cb[k][t].y); }
;             }
;         }
.Lsd0_loop:
	s_add_i32 s37, s39, 3
	s_min_u32 s37, s37, 0x7f
	s_lshl_b32 s38, s37, 13
	s_add_u32 s82, s44, s38
	s_addc_u32 s83, s45, 0
	global_load_dwordx2 v[48:49], v6, s[82:83]
	global_load_dwordx2 v[50:51], v6, s[82:83] offset:512
	global_load_dwordx2 v[52:53], v6, s[82:83] offset:1024
	global_load_dwordx2 v[54:55], v6, s[82:83] offset:1536
	s_waitcnt vmcnt(24)
	v_cvt_pk_bf16_f32 v120, v8, v9
	v_cvt_pk_bf16_f32 v121, v10, v11
	v_cvt_pk_bf16_f32 v122, v12, v13
	v_cvt_pk_bf16_f32 v123, v14, v15
	v_cvt_pk_bf16_f32 v124, v16, v17
	v_cvt_pk_bf16_f32 v125, v18, v19
	v_cvt_pk_bf16_f32 v126, v20, v21
	v_cvt_pk_bf16_f32 v127, v22, v23
	s_add_i32 s37, s39, 0
	s_lshl_b32 s38, s37, 13
	s_add_u32 s40, s44, s38
	s_addc_u32 s41, s45, 0
	global_store_dwordx2 v6, v[120:121], s[40:41] nt
	global_store_dwordx2 v6, v[122:123], s[40:41] offset:512 nt
	global_store_dwordx2 v6, v[124:125], s[40:41] offset:1024 nt
	global_store_dwordx2 v6, v[126:127], s[40:41] offset:1536 nt
	v_lshlrev_b32_e32 v128, 16, v24
	v_and_b32_e32 v129, 0xffff0000, v24
	v_lshlrev_b32_e32 v130, 16, v25
	v_and_b32_e32 v131, 0xffff0000, v25
	v_fma_f32 v8, v0, v8, v128
	v_fma_f32 v9, v0, v9, v129
	v_fma_f32 v10, v0, v10, v130
	v_fma_f32 v11, v0, v11, v131
	v_lshlrev_b32_e32 v128, 16, v26
	v_and_b32_e32 v129, 0xffff0000, v26
	v_lshlrev_b32_e32 v130, 16, v27
	v_and_b32_e32 v131, 0xffff0000, v27
	v_fma_f32 v12, v0, v12, v128
	v_fma_f32 v13, v0, v13, v129
	v_fma_f32 v14, v0, v14, v130
	v_fma_f32 v15, v0, v15, v131
	v_lshlrev_b32_e32 v128, 16, v28
	v_and_b32_e32 v129, 0xffff0000, v28
	v_lshlrev_b32_e32 v130, 16, v29
	v_and_b32_e32 v131, 0xffff0000, v29
	v_fma_f32 v16, v0, v16, v128
	v_fma_f32 v17, v0, v17, v129
	v_fma_f32 v18, v0, v18, v130
	v_fma_f32 v19, v0, v19, v131
	v_lshlrev_b32_e32 v128, 16, v30
	v_and_b32_e32 v129, 0xffff0000, v30
	v_lshlrev_b32_e32 v130, 16, v31
	v_and_b32_e32 v131, 0xffff0000, v31
	v_fma_f32 v20, v0, v20, v128
	v_fma_f32 v21, v0, v21, v129
	v_fma_f32 v22, v0, v22, v130
	v_fma_f32 v23, v0, v23, v131
	s_add_i32 s37, s39, 4
	s_min_u32 s37, s37, 0x7f
	s_lshl_b32 s38, s37, 13
	s_add_u32 s82, s44, s38
	s_addc_u32 s83, s45, 0
	global_load_dwordx2 v[24:25], v6, s[82:83]
	global_load_dwordx2 v[26:27], v6, s[82:83] offset:512
	global_load_dwordx2 v[28:29], v6, s[82:83] offset:1024
	global_load_dwordx2 v[30:31], v6, s[82:83] offset:1536
	s_waitcnt vmcnt(24)
	v_cvt_pk_bf16_f32 v120, v8, v9
	v_cvt_pk_bf16_f32 v121, v10, v11
	v_cvt_pk_bf16_f32 v122, v12, v13
	v_cvt_pk_bf16_f32 v123, v14, v15
	v_cvt_pk_bf16_f32 v124, v16, v17
	v_cvt_pk_bf16_f32 v125, v18, v19
	v_cvt_pk_bf16_f32 v126, v20, v21
	v_cvt_pk_bf16_f32 v127, v22, v23
	s_add_i32 s37, s39, 1
	s_lshl_b32 s38, s37, 13
	s_add_u32 s40, s44, s38
	s_addc_u32 s41, s45, 0
	global_store_dwordx2 v6, v[120:121], s[40:41] nt
	global_store_dwordx2 v6, v[122:123], s[40:41] offset:512 nt
	global_store_dwordx2 v6, v[124:125], s[40:41] offset:1024 nt
	global_store_dwordx2 v6, v[126:127], s[40:41] offset:1536 nt
	v_lshlrev_b32_e32 v128, 16, v32
	v_and_b32_e32 v129, 0xffff0000, v32
	v_lshlrev_b32_e32 v130, 16, v33
	v_and_b32_e32 v131, 0xffff0000, v33
	v_fma_f32 v8, v0, v8, v128
	v_fma_f32 v9, v0, v9, v129
	v_fma_f32 v10, v0, v10, v130
	v_fma_f32 v11, v0, v11, v131
	v_lshlrev_b32_e32 v128, 16, v34
	v_and_b32_e32 v129, 0xffff0000, v34
	v_lshlrev_b32_e32 v130, 16, v35
	v_and_b32_e32 v131, 0xffff0000, v35
	v_fma_f32 v12, v0, v12, v128
	v_fma_f32 v13, v0, v13, v129
	v_fma_f32 v14, v0, v14, v130
	v_fma_f32 v15, v0, v15, v131
	v_lshlrev_b32_e32 v128, 16, v36
	v_and_b32_e32 v129, 0xffff0000, v36
	v_lshlrev_b32_e32 v130, 16, v37
	v_and_b32_e32 v131, 0xffff0000, v37
	v_fma_f32 v16, v0, v16, v128
	v_fma_f32 v17, v0, v17, v129
	v_fma_f32 v18, v0, v18, v130
	v_fma_f32 v19, v0, v19, v131
	v_lshlrev_b32_e32 v128, 16, v38
	v_and_b32_e32 v129, 0xffff0000, v38
	v_lshlrev_b32_e32 v130, 16, v39
	v_and_b32_e32 v131, 0xffff0000, v39
	v_fma_f32 v20, v0, v20, v128
	v_fma_f32 v21, v0, v21, v129
	v_fma_f32 v22, v0, v22, v130
	v_fma_f32 v23, v0, v23, v131
	s_add_i32 s37, s39, 5
	s_min_u32 s37, s37, 0x7f
	s_lshl_b32 s38, s37, 13
	s_add_u32 s82, s44, s38
	s_addc_u32 s83, s45, 0
	global_load_dwordx2 v[32:33], v6, s[82:83]
	global_load_dwordx2 v[34:35], v6, s[82:83] offset:512
	global_load_dwordx2 v[36:37], v6, s[82:83] offset:1024
	global_load_dwordx2 v[38:39], v6, s[82:83] offset:1536
	s_waitcnt vmcnt(24)
; __device__ __forceinline__ float bf_lo(unsigned u) { return __uint_as_float(u << 16); }
; __device__ __forceinline__ float bf_hi(unsigned u) { return __uint_as_float(u & 0xffff0000u); }
; __device__ __forceinline__ unsigned pk2(float lo, float hi) { return pg8::cvt_pk_bf16(lo, hi); }
; #define SCAN_LOAD_D(slot, cc) { const int c_ = (cc) < NCH ? (cc) : NCH - 1; const bf16_t* bcn = bc0 + (size_t)c_ * 4096; \
;             _Pragma("unroll") for (int t = 0; t < 4; ++t) { cb[slot][t] = *(const u32x2*)(bcn + 256 * t); cm[slot][t] = mixer == 2 ? *(const f32x4*)(mv0 + (size_t)c_ * 64 + 16 * t) : (f32x4){g64, g64, g64, g64}; } }
; __device__ __forceinline__ void scan_phase(const Ctx& X, int wave, int lane) {
;     ...
;         SCAN_LOAD_D(0, 0) SCAN_LOAD_D(1, 1) SCAN_LOAD_D(2, 2)
; #pragma unroll 1
;         for (int c0 = 0; c0 < NCH; c0 += 4) {
; #pragma unroll
;             for (int k = 0; k < 4; ++k) {
;                 const int c = c0 + k;
;                 SCAN_LOAD_D((k + 3) & 3, c + 3)
;                 bf16_t* bcc = bc0 + (size_t)c * 4096;
; #pragma unroll
;                 for (int t = 0; t < 4; ++t) { u32x2 sp; sp.x = pk2(S[t][0], S[t][1]); sp.y = pk2(S[t][2], S[t][3]);
;                     asm volatile("" : "+v"(sp.x) : "v"(cb[k][t].x));
;                     *(u32x2*)(bcc + 256 * t) = sp;
;                     S[t][0] = cm[k][t].x * S[t][0] + bf_lo(cb[k][t].x); S[t][1] = cm[k][t].y * S[t][1] + bf_hi(cb[k][t].x);
;                     S[t][2] = cm[k][t].z * S[t][2] + bf_lo(cb[k][t].y); S[t][3] = cm[k][t].w * S[t][3] + bf_hi(cb[k][t].y); }
;             }
;         }
	v_cvt_pk_bf16_f32 v120, v8, v9
	v_cvt_pk_bf16_f32 v121, v10, v11
	v_cvt_pk_bf16_f32 v122, v12, v13
	v_cvt_pk_bf16_f32 v123, v14, v15
	v_cvt_pk_bf16_f32 v124, v16, v17
	v_cvt_pk_bf16_f32 v125, v18, v19
	v_cvt_pk_bf16_f32 v126, v20, v21
	v_cvt_pk_bf16_f32 v127, v22, v23
	s_add_i32 s37, s39, 2
	s_lshl_b32 s38, s37, 13
	s_add_u32 s40, s44, s38
	s_addc_u32 s41, s45, 0
	global_store_dwordx2 v6, v[120:121], s[40:41] nt
	global_store_dwordx2 v6, v[122:123], s[40:41] offset:512 nt
	global_store_dwordx2 v6, v[124:125], s[40:41] offset:1024 nt
	global_store_dwordx2 v6, v[126:127], s[40:41] offset:1536 nt
	v_lshlrev_b32_e32 v128, 16, v40
	v_and_b32_e32 v129, 0xffff0000, v40
	v_lshlrev_b32_e32 v130, 16, v41
	v_and_b32_e32 v131, 0xffff0000, v41
	v_fma_f32 v8, v0, v8, v128
	v_fma_f32 v9, v0, v9, v129
	v_fma_f32 v10, v0, v10, v130
	v_fma_f32 v11, v0, v11, v131
	v_lshlrev_b32_e32 v128, 16, v42
	v_and_b32_e32 v129, 0xffff0000, v42
	v_lshlrev_b32_e32 v130, 16, v43
	v_and_b32_e32 v131, 0xffff0000, v43
	v_fma_f32 v12, v0, v12, v128
	v_fma_f32 v13, v0, v13, v129
	v_fma_f32 v14, v0, v14, v130
	v_fma_f32 v15, v0, v15, v131
	v_lshlrev_b32_e32 v128, 16, v44
	v_and_b32_e32 v129, 0xffff0000, v44
	v_lshlrev_b32_e32 v130, 16, v45
	v_and_b32_e32 v131, 0xffff0000, v45
	v_fma_f32 v16, v0, v16, v128
	v_fma_f32 v17, v0, v17, v129
	v_fma_f32 v18, v0, v18, v130
	v_fma_f32 v19, v0, v19, v131
	v_lshlrev_b32_e32 v128, 16, v46
	v_and_b32_e32 v129, 0xffff0000, v46
	v_lshlrev_b32_e32 v130, 16, v47
	v_and_b32_e32 v131, 0xffff0000, v47
	v_fma_f32 v20, v0, v20, v128
	v_fma_f32 v21, v0, v21, v129
	v_fma_f32 v22, v0, v22, v130
	v_fma_f32 v23, v0, v23, v131
	s_add_i32 s37, s39, 6
	s_min_u32 s37, s37, 0x7f
	s_lshl_b32 s38, s37, 13
	s_add_u32 s82, s44, s38
	s_addc_u32 s83, s45, 0
	global_load_dwordx2 v[40:41], v6, s[82:83]
	global_load_dwordx2 v[42:43], v6, s[82:83] offset:512
	global_load_dwordx2 v[44:45], v6, s[82:83] offset:1024
	global_load_dwordx2 v[46:47], v6, s[82:83] offset:1536
	s_waitcnt vmcnt(24)
	v_cvt_pk_bf16_f32 v120, v8, v9
	v_cvt_pk_bf16_f32 v121, v10, v11
	v_cvt_pk_bf16_f32 v122, v12, v13
	v_cvt_pk_bf16_f32 v123, v14, v15
	v_cvt_pk_bf16_f32 v124, v16, v17
	v_cvt_pk_bf16_f32 v125, v18, v19
	v_cvt_pk_bf16_f32 v126, v20, v21
	v_cvt_pk_bf16_f32 v127, v22, v23
	s_add_i32 s37, s39, 3
	s_lshl_b32 s38, s37, 13
	s_add_u32 s40, s44, s38
	s_addc_u32 s41, s45, 0
	global_store_dwordx2 v6, v[120:121], s[40:41] nt
	global_store_dwordx2 v6, v[122:123], s[40:41] offset:512 nt
	global_store_dwordx2 v6, v[124:125], s[40:41] offset:1024 nt
	global_store_dwordx2 v6, v[126:127], s[40:41] offset:1536 nt
	v_lshlrev_b32_e32 v128, 16, v48
	v_and_b32_e32 v129, 0xffff0000, v48
	v_lshlrev_b32_e32 v130, 16, v49
	v_and_b32_e32 v131, 0xffff0000, v49
	v_fma_f32 v8, v0, v8, v128
	v_fma_f32 v9, v0, v9, v129
	v_fma_f32 v10, v0, v10, v130
	v_fma_f32 v11, v0, v11, v131
	v_lshlrev_b32_e32 v128, 16, v50
	v_and_b32_e32 v129, 0xffff0000, v50
	v_lshlrev_b32_e32 v130, 16, v51
	v_and_b32_e32 v131, 0xffff0000, v51
	v_fma_f32 v12, v0, v12, v128
	v_fma_f32 v13, v0, v13, v129
	v_fma_f32 v14, v0, v14, v130
	v_fma_f32 v15, v0, v15, v131
	v_lshlrev_b32_e32 v128, 16, v52
	v_and_b32_e32 v129, 0xffff0000, v52
	v_lshlrev_b32_e32 v130, 16, v53
	v_and_b32_e32 v131, 0xffff0000, v53
	v_fma_f32 v16, v0, v16, v128
	v_fma_f32 v17, v0, v17, v129
	v_fma_f32 v18, v0, v18, v130
	v_fma_f32 v19, v0, v19, v131
	v_lshlrev_b32_e32 v128, 16, v54
	v_and_b32_e32 v129, 0xffff0000, v54
	v_lshlrev_b32_e32 v130, 16, v55
	v_and_b32_e32 v131, 0xffff0000, v55
	v_fma_f32 v20, v0, v20, v128
	v_fma_f32 v21, v0, v21, v129
	v_fma_f32 v22, v0, v22, v130
	v_fma_f32 v23, v0, v23, v131
	s_add_i32 s39, s39, 4
	s_cmpk_lt_u32 s39, 0x80
	s_cbranch_scc1 .Lsd0_loop
	s_branch .LBB0_739

; __device__ __forceinline__ float bf_lo(unsigned u) { return __uint_as_float(u << 16); }
; __device__ __forceinline__ float bf_hi(unsigned u) { return __uint_as_float(u & 0xffff0000u); }
; __device__ __forceinline__ unsigned pk2(float lo, float hi) { return pg8::cvt_pk_bf16(lo, hi); }
; #define SCAN_LOAD_D(slot, cc) { const int c_ = (cc) < NCH ? (cc) : NCH - 1; const bf16_t* bcn = bc0 + (size_t)c_ * 4096; \
;             _Pragma("unroll") for (int t = 0; t < 4; ++t) { cb[slot][t] = *(const u32x2*)(bcn + 256 * t); cm[slot][t] = mixer == 2 ? *(const f32x4*)(mv0 + (size_t)c_ * 64 + 16 * t) : (f32x4){g64, g64, g64, g64}; } }
; __device__ __forceinline__ void scan_phase(const Ctx& X, int wave, int lane) {
;     ...
;         SCAN_LOAD_D(0, 0) SCAN_LOAD_D(1, 1) SCAN_LOAD_D(2, 2)
; #pragma unroll 1
;         for (int c0 = 0; c0 < NCH; c0 += 4) {
; #pragma unroll
;             for (int k = 0; k < 4; ++k) {
;                 const int c = c0 + k;
;                 SCAN_LOAD_D((k + 3) & 3, c + 3)
;                 bf16_t* bcc = bc0 + (size_t)c * 4096;
; #pragma unroll
;                 for (int t = 0; t < 4; ++t) { u32x2 sp; sp.x = pk2(S[t][0], S[t][1]); sp.y = pk2(S[t][2], S[t][3]);
;                     asm volatile("" : "+v"(sp.x) : "v"(cb[k][t].x));
;                     *(u32x2*)(bcc + 256 * t) = sp;
;                     S[t][0] = cm[k][t].x * S[t][0] + bf_lo(cb[k][t].x); S[t][1] = cm[k][t].y * S[t][1] + bf_hi(cb[k][t].x);
;                     S[t][2] = cm[k][t].z * S[t][2] + bf_lo(cb[k][t].y); S[t][3] = cm[k][t].w * S[t][3] + bf_hi(cb[k][t].y); }
;             }
;         }
.Lsd2_loop:
	s_add_i32 s37, s39, 3
	s_min_u32 s37, s37, 0x7f
	s_lshl_b32 s38, s37, 13
	s_add_u32 s82, s44, s38
	s_addc_u32 s83, s45, 0
	global_load_dwordx2 v[48:49], v6, s[82:83]
	global_load_dwordx2 v[50:51], v6, s[82:83] offset:512
	global_load_dwordx2 v[52:53], v6, s[82:83] offset:1024
	global_load_dwordx2 v[54:55], v6, s[82:83] offset:1536
	s_lshl_b32 s38, s37, 8
	s_add_u32 s82, s46, s38
	s_addc_u32 s83, s47, 0
	global_load_dwordx4 v[104:107], v7, s[82:83]
	global_load_dwordx4 v[108:111], v7, s[82:83] offset:64
	global_load_dwordx4 v[112:115], v7, s[82:83] offset:128
	global_load_dwordx4 v[116:119], v7, s[82:83] offset:192
	s_waitcnt vmcnt(36)
	v_cvt_pk_bf16_f32 v120, v8, v9
	v_cvt_pk_bf16_f32 v121, v10, v11
	v_cvt_pk_bf16_f32 v122, v12, v13
	v_cvt_pk_bf16_f32 v123, v14, v15
	v_cvt_pk_bf16_f32 v124, v16, v17
	v_cvt_pk_bf16_f32 v125, v18, v19
	v_cvt_pk_bf16_f32 v126, v20, v21
	v_cvt_pk_bf16_f32 v127, v22, v23
	s_add_i32 s37, s39, 0
	s_lshl_b32 s38, s37, 13
	s_add_u32 s40, s44, s38
	s_addc_u32 s41, s45, 0
	global_store_dwordx2 v6, v[120:121], s[40:41] nt
	global_store_dwordx2 v6, v[122:123], s[40:41] offset:512 nt
	global_store_dwordx2 v6, v[124:125], s[40:41] offset:1024 nt
	global_store_dwordx2 v6, v[126:127], s[40:41] offset:1536 nt
	v_lshlrev_b32_e32 v128, 16, v24
	v_and_b32_e32 v129, 0xffff0000, v24
	v_lshlrev_b32_e32 v130, 16, v25
	v_and_b32_e32 v131, 0xffff0000, v25
	v_fma_f32 v8, v56, v8, v128
	v_fma_f32 v9, v57, v9, v129
	v_fma_f32 v10, v58, v10, v130
	v_fma_f32 v11, v59, v11, v131
	v_lshlrev_b32_e32 v128, 16, v26
	v_and_b32_e32 v129, 0xffff0000, v26
	v_lshlrev_b32_e32 v130, 16, v27
	v_and_b32_e32 v131, 0xffff0000, v27
	v_fma_f32 v12, v60, v12, v128
	v_fma_f32 v13, v61, v13, v129
	v_fma_f32 v14, v62, v14, v130
	v_fma_f32 v15, v63, v15, v131
	v_lshlrev_b32_e32 v128, 16, v28
	v_and_b32_e32 v129, 0xffff0000, v28
	v_lshlrev_b32_e32 v130, 16, v29
	v_and_b32_e32 v131, 0xffff0000, v29
	v_fma_f32 v16, v64, v16, v128
	v_fma_f32 v17, v65, v17, v129
	v_fma_f32 v18, v66, v18, v130
	v_fma_f32 v19, v67, v19, v131
	v_lshlrev_b32_e32 v128, 16, v30
	v_and_b32_e32 v129, 0xffff0000, v30
	v_lshlrev_b32_e32 v130, 16, v31
	v_and_b32_e32 v131, 0xffff0000, v31
	v_fma_f32 v20, v68, v20, v128
	v_fma_f32 v21, v69, v21, v129
	v_fma_f32 v22, v70, v22, v130
	v_fma_f32 v23, v71, v23, v131
	s_add_i32 s37, s39, 4
	s_min_u32 s37, s37, 0x7f
	s_lshl_b32 s38, s37, 13
	s_add_u32 s82, s44, s38
	s_addc_u32 s83, s45, 0
	global_load_dwordx2 v[24:25], v6, s[82:83]
	global_load_dwordx2 v[26:27], v6, s[82:83] offset:512
	global_load_dwordx2 v[28:29], v6, s[82:83] offset:1024
	global_load_dwordx2 v[30:31], v6, s[82:83] offset:1536
	s_lshl_b32 s38, s37, 8
	s_add_u32 s82, s46, s38
	s_addc_u32 s83, s47, 0
	global_load_dwordx4 v[56:59], v7, s[82:83]
	global_load_dwordx4 v[60:63], v7, s[82:83] offset:64
	global_load_dwordx4 v[64:67], v7, s[82:83] offset:128
	global_load_dwordx4 v[68:71], v7, s[82:83] offset:192
	s_waitcnt vmcnt(36)
	v_cvt_pk_bf16_f32 v120, v8, v9
	v_cvt_pk_bf16_f32 v121, v10, v11
	v_cvt_pk_bf16_f32 v122, v12, v13
	v_cvt_pk_bf16_f32 v123, v14, v15
	v_cvt_pk_bf16_f32 v124, v16, v17
	v_cvt_pk_bf16_f32 v125, v18, v19
	v_cvt_pk_bf16_f32 v126, v20, v21
	v_cvt_pk_bf16_f32 v127, v22, v23
	s_add_i32 s37, s39, 1
	s_lshl_b32 s38, s37, 13
	s_add_u32 s40, s44, s38
	s_addc_u32 s41, s45, 0
	global_store_dwordx2 v6, v[120:121], s[40:41] nt
	global_store_dwordx2 v6, v[122:123], s[40:41] offset:512 nt
	global_store_dwordx2 v6, v[124:125], s[40:41] offset:1024 nt
	global_store_dwordx2 v6, v[126:127], s[40:41] offset:1536 nt
	v_lshlrev_b32_e32 v128, 16, v32
	v_and_b32_e32 v129, 0xffff0000, v32
	v_lshlrev_b32_e32 v130, 16, v33
	v_and_b32_e32 v131, 0xffff0000, v33
	v_fma_f32 v8, v72, v8, v128
	v_fma_f32 v9, v73, v9, v129
	v_fma_f32 v10, v74, v10, v130
	v_fma_f32 v11, v75, v11, v131
	v_lshlrev_b32_e32 v128, 16, v34
	v_and_b32_e32 v129, 0xffff0000, v34
	v_lshlrev_b32_e32 v130, 16, v35
	v_and_b32_e32 v131, 0xffff0000, v35
	v_fma_f32 v12, v76, v12, v128
	v_fma_f32 v13, v77, v13, v129
	v_fma_f32 v14, v78, v14, v130
	v_fma_f32 v15, v79, v15, v131
	v_lshlrev_b32_e32 v128, 16, v36
	v_and_b32_e32 v129, 0xffff0000, v36
	v_lshlrev_b32_e32 v130, 16, v37
	v_and_b32_e32 v131, 0xffff0000, v37
	v_fma_f32 v16, v80, v16, v128
	v_fma_f32 v17, v81, v17, v129
	v_fma_f32 v18, v82, v18, v130
	v_fma_f32 v19, v83, v19, v131
	v_lshlrev_b32_e32 v128, 16, v38
	v_and_b32_e32 v129, 0xffff0000, v38
	v_lshlrev_b32_e32 v130, 16, v39
	v_and_b32_e32 v131, 0xffff0000, v39
	v_fma_f32 v20, v84, v20, v128
	v_fma_f32 v21, v85, v21, v129
	v_fma_f32 v22, v86, v22, v130
	v_fma_f32 v23, v87, v23, v131
	s_add_i32 s37, s39, 5
	s_min_u32 s37, s37, 0x7f
	s_lshl_b32 s38, s37, 13
	s_add_u32 s82, s44, s38
	s_addc_u32 s83, s45, 0
	global_load_dwordx2 v[32:33], v6, s[82:83]
	global_load_dwordx2 v[34:35], v6, s[82:83] offset:512
	global_load_dwordx2 v[36:37], v6, s[82:83] offset:1024
	global_load_dwordx2 v[38:39], v6, s[82:83] offset:1536
	s_lshl_b32 s38, s37, 8
	s_add_u32 s82, s46, s38
	s_addc_u32 s83, s47, 0
	global_load_dwordx4 v[72:75], v7, s[82:83]
	global_load_dwordx4 v[76:79], v7, s[82:83] offset:64
	global_load_dwordx4 v[80:83], v7, s[82:83] offset:128
	global_load_dwordx4 v[84:87], v7, s[82:83] offset:192
	s_waitcnt vmcnt(36)
; __device__ __forceinline__ float bf_lo(unsigned u) { return __uint_as_float(u << 16); }
; __device__ __forceinline__ float bf_hi(unsigned u) { return __uint_as_float(u & 0xffff0000u); }
; __device__ __forceinline__ unsigned pk2(float lo, float hi) { return pg8::cvt_pk_bf16(lo, hi); }
; #define SCAN_LOAD_D(slot, cc) { const int c_ = (cc) < NCH ? (cc) : NCH - 1; const bf16_t* bcn = bc0 + (size_t)c_ * 4096; \
;             _Pragma("unroll") for (int t = 0; t < 4; ++t) { cb[slot][t] = *(const u32x2*)(bcn + 256 * t); cm[slot][t] = mixer == 2 ? *(const f32x4*)(mv0 + (size_t)c_ * 64 + 16 * t) : (f32x4){g64, g64, g64, g64}; } }
; __device__ __forceinline__ void scan_phase(const Ctx& X, int wave, int lane) {
;     ...
;         SCAN_LOAD_D(0, 0) SCAN_LOAD_D(1, 1) SCAN_LOAD_D(2, 2)
; #pragma unroll 1
;         for (int c0 = 0; c0 < NCH; c0 += 4) {
; #pragma unroll
;             for (int k = 0; k < 4; ++k) {
;                 const int c = c0 + k;
;                 SCAN_LOAD_D((k + 3) & 3, c + 3)
;                 bf16_t* bcc = bc0 + (size_t)c * 4096;
; #pragma unroll
;                 for (int t = 0; t < 4; ++t) { u32x2 sp; sp.x = pk2(S[t][0], S[t][1]); sp.y = pk2(S[t][2], S[t][3]);
;                     asm volatile("" : "+v"(sp.x) : "v"(cb[k][t].x));
;                     *(u32x2*)(bcc + 256 * t) = sp;
;                     S[t][0] = cm[k][t].x * S[t][0] + bf_lo(cb[k][t].x); S[t][1] = cm[k][t].y * S[t][1] + bf_hi(cb[k][t].x);
;                     S[t][2] = cm[k][t].z * S[t][2] + bf_lo(cb[k][t].y); S[t][3] = cm[k][t].w * S[t][3] + bf_hi(cb[k][t].y); }
;             }
;         }
	v_cvt_pk_bf16_f32 v120, v8, v9
	v_cvt_pk_bf16_f32 v121, v10, v11
	v_cvt_pk_bf16_f32 v122, v12, v13
	v_cvt_pk_bf16_f32 v123, v14, v15
	v_cvt_pk_bf16_f32 v124, v16, v17
	v_cvt_pk_bf16_f32 v125, v18, v19
	v_cvt_pk_bf16_f32 v126, v20, v21
	v_cvt_pk_bf16_f32 v127, v22, v23
	s_add_i32 s37, s39, 2
	s_lshl_b32 s38, s37, 13
	s_add_u32 s40, s44, s38
	s_addc_u32 s41, s45, 0
	global_store_dwordx2 v6, v[120:121], s[40:41] nt
	global_store_dwordx2 v6, v[122:123], s[40:41] offset:512 nt
	global_store_dwordx2 v6, v[124:125], s[40:41] offset:1024 nt
	global_store_dwordx2 v6, v[126:127], s[40:41] offset:1536 nt
	v_lshlrev_b32_e32 v128, 16, v40
	v_and_b32_e32 v129, 0xffff0000, v40
	v_lshlrev_b32_e32 v130, 16, v41
	v_and_b32_e32 v131, 0xffff0000, v41
	v_fma_f32 v8, v88, v8, v128
	v_fma_f32 v9, v89, v9, v129
	v_fma_f32 v10, v90, v10, v130
	v_fma_f32 v11, v91, v11, v131
	v_lshlrev_b32_e32 v128, 16, v42
	v_and_b32_e32 v129, 0xffff0000, v42
	v_lshlrev_b32_e32 v130, 16, v43
	v_and_b32_e32 v131, 0xffff0000, v43
	v_fma_f32 v12, v92, v12, v128
	v_fma_f32 v13, v93, v13, v129
	v_fma_f32 v14, v94, v14, v130
	v_fma_f32 v15, v95, v15, v131
	v_lshlrev_b32_e32 v128, 16, v44
	v_and_b32_e32 v129, 0xffff0000, v44
	v_lshlrev_b32_e32 v130, 16, v45
	v_and_b32_e32 v131, 0xffff0000, v45
	v_fma_f32 v16, v96, v16, v128
	v_fma_f32 v17, v97, v17, v129
	v_fma_f32 v18, v98, v18, v130
	v_fma_f32 v19, v99, v19, v131
	v_lshlrev_b32_e32 v128, 16, v46
	v_and_b32_e32 v129, 0xffff0000, v46
	v_lshlrev_b32_e32 v130, 16, v47
	v_and_b32_e32 v131, 0xffff0000, v47
	v_fma_f32 v20, v100, v20, v128
	v_fma_f32 v21, v101, v21, v129
	v_fma_f32 v22, v102, v22, v130
	v_fma_f32 v23, v103, v23, v131
	s_add_i32 s37, s39, 6
	s_min_u32 s37, s37, 0x7f
	s_lshl_b32 s38, s37, 13
	s_add_u32 s82, s44, s38
	s_addc_u32 s83, s45, 0
	global_load_dwordx2 v[40:41], v6, s[82:83]
	global_load_dwordx2 v[42:43], v6, s[82:83] offset:512
	global_load_dwordx2 v[44:45], v6, s[82:83] offset:1024
	global_load_dwordx2 v[46:47], v6, s[82:83] offset:1536
	s_lshl_b32 s38, s37, 8
	s_add_u32 s82, s46, s38
	s_addc_u32 s83, s47, 0
	global_load_dwordx4 v[88:91], v7, s[82:83]
	global_load_dwordx4 v[92:95], v7, s[82:83] offset:64
	global_load_dwordx4 v[96:99], v7, s[82:83] offset:128
	global_load_dwordx4 v[100:103], v7, s[82:83] offset:192
	s_waitcnt vmcnt(36)
	v_cvt_pk_bf16_f32 v120, v8, v9
	v_cvt_pk_bf16_f32 v121, v10, v11
	v_cvt_pk_bf16_f32 v122, v12, v13
	v_cvt_pk_bf16_f32 v123, v14, v15
	v_cvt_pk_bf16_f32 v124, v16, v17
	v_cvt_pk_bf16_f32 v125, v18, v19
	v_cvt_pk_bf16_f32 v126, v20, v21
	v_cvt_pk_bf16_f32 v127, v22, v23
	s_add_i32 s37, s39, 3
	s_lshl_b32 s38, s37, 13
	s_add_u32 s40, s44, s38
	s_addc_u32 s41, s45, 0
	global_store_dwordx2 v6, v[120:121], s[40:41] nt
	global_store_dwordx2 v6, v[122:123], s[40:41] offset:512 nt
	global_store_dwordx2 v6, v[124:125], s[40:41] offset:1024 nt
	global_store_dwordx2 v6, v[126:127], s[40:41] offset:1536 nt
	v_lshlrev_b32_e32 v128, 16, v48
	v_and_b32_e32 v129, 0xffff0000, v48
	v_lshlrev_b32_e32 v130, 16, v49
	v_and_b32_e32 v131, 0xffff0000, v49
	v_fma_f32 v8, v104, v8, v128
	v_fma_f32 v9, v105, v9, v129
	v_fma_f32 v10, v106, v10, v130
	v_fma_f32 v11, v107, v11, v131
	v_lshlrev_b32_e32 v128, 16, v50
	v_and_b32_e32 v129, 0xffff0000, v50
	v_lshlrev_b32_e32 v130, 16, v51
	v_and_b32_e32 v131, 0xffff0000, v51
	v_fma_f32 v12, v108, v12, v128
	v_fma_f32 v13, v109, v13, v129
	v_fma_f32 v14, v110, v14, v130
	v_fma_f32 v15, v111, v15, v131
	v_lshlrev_b32_e32 v128, 16, v52
	v_and_b32_e32 v129, 0xffff0000, v52
	v_lshlrev_b32_e32 v130, 16, v53
	v_and_b32_e32 v131, 0xffff0000, v53
	v_fma_f32 v16, v112, v16, v128
	v_fma_f32 v17, v113, v17, v129
	v_fma_f32 v18, v114, v18, v130
	v_fma_f32 v19, v115, v19, v131
	v_lshlrev_b32_e32 v128, 16, v54
	v_and_b32_e32 v129, 0xffff0000, v54
	v_lshlrev_b32_e32 v130, 16, v55
	v_and_b32_e32 v131, 0xffff0000, v55
	v_fma_f32 v20, v116, v20, v128
	v_fma_f32 v21, v117, v21, v129
	v_fma_f32 v22, v118, v22, v130
	v_fma_f32 v23, v119, v23, v131
	s_add_i32 s39, s39, 4
	s_cmpk_lt_u32 s39, 0x80
	s_cbranch_scc1 .Lsd2_loop
	s_branch .LBB0_739

; __device__ __forceinline__ float bf_lo(unsigned u) { return __uint_as_float(u << 16); }
; __device__ __forceinline__ float bf_hi(unsigned u) { return __uint_as_float(u & 0xffff0000u); }
; __device__ __forceinline__ unsigned pk2(float lo, float hi) { return pg8::cvt_pk_bf16(lo, hi); }
; __device__ __forceinline__ void scan_phase(const Ctx& X, int wave, int lane) {
;     ...
;         SCAN_LOAD_G(0, 0) SCAN_LOAD_G(1, 1) SCAN_LOAD_G(2, 2)
; #pragma unroll 1
;         for (int c0 = 0; c0 < NCH; c0 += 4) {
; #pragma unroll
;             for (int k = 0; k < 4; ++k) {
;                 const int c = c0 + k;
;                 SCAN_LOAD_G((k + 3) & 3, c + 3)
;                 bf16_t* bcc = bc0 + (size_t)c * 4096;
;                 u32x2 sp[4];
; #pragma unroll
;                 for (int t = 0; t < 4; ++t) { sp[t].x = pk2(S[t][0], S[t][1]); sp[t].y = pk2(S[t][2], S[t][3]);
;                     asm volatile("" : "+v"(sp[t].x) : "v"(cb[k][t].x));
;                     *(u32x2*)(bcc + 256 * t) = sp[t]; }
;                 bf16x8 bfr[2];
; #pragma unroll
;                 for (int s2 = 0; s2 < 2; ++s2) { u32x4 w; w.x = sp[2 * s2].x; w.y = sp[2 * s2].y; w.z = sp[2 * s2 + 1].x; w.w = sp[2 * s2 + 1].y; bfr[s2] = __builtin_bit_cast(bf16x8, w); }
; #pragma unroll
;                 for (int t = 0; t < 4; ++t) {
;                     f32x4 acc = (f32x4){bf_lo(cb[k][t].x), bf_hi(cb[k][t].x), bf_lo(cb[k][t].y), bf_hi(cb[k][t].y)};
; #pragma unroll
;                     for (int s2 = 0; s2 < 2; ++s2) { u32x4 w; w.x = ca[k][t][s2][0].x; w.y = ca[k][t][s2][0].y; w.z = ca[k][t][s2][1].x; w.w = ca[k][t][s2][1].y;
;                         acc = __builtin_amdgcn_mfma_f32_16x16x32_bf16(__builtin_bit_cast(bf16x8, w), bfr[s2], acc, 0, 0, 0); }
;                     S[t][0] = acc[0]; S[t][1] = acc[1]; S[t][2] = acc[2]; S[t][3] = acc[3];
;                 }
;             }
;         }
.Lsg_loop:
	s_add_i32 s37, s39, 3
	s_min_u32 s37, s37, 0x7f
	s_lshl_b32 s38, s37, 13
	s_add_u32 s82, s44, s38
	s_addc_u32 s83, s45, 0
	global_load_dwordx2 v[48:49], v6, s[82:83]
	global_load_dwordx2 v[50:51], v6, s[82:83] offset:512
	global_load_dwordx2 v[52:53], v6, s[82:83] offset:1024
	global_load_dwordx2 v[54:55], v6, s[82:83] offset:1536
	s_add_u32 s82, s46, s38
	s_addc_u32 s83, s47, 0
	global_load_dwordx4 v[176:179], v7, s[82:83]
	global_load_dwordx4 v[184:187], v7, s[82:83] offset:1024
	global_load_dwordx4 v[188:191], v7, s[82:83] offset:2048
	global_load_dwordx4 v[192:195], v7, s[82:83] offset:3072
	global_load_dwordx4 v[196:199], v129, s[82:83]
	global_load_dwordx4 v[200:203], v129, s[82:83] offset:1024
	global_load_dwordx4 v[204:207], v129, s[82:83] offset:2048
	global_load_dwordx4 v[208:211], v129, s[82:83] offset:3072
	s_waitcnt vmcnt(56)
	v_cvt_pk_bf16_f32 v120, v8, v9
	v_cvt_pk_bf16_f32 v121, v10, v11
	v_cvt_pk_bf16_f32 v122, v12, v13
	v_cvt_pk_bf16_f32 v123, v14, v15
	v_cvt_pk_bf16_f32 v124, v16, v17
	v_cvt_pk_bf16_f32 v125, v18, v19
	v_cvt_pk_bf16_f32 v126, v20, v21
	v_cvt_pk_bf16_f32 v127, v22, v23
	s_add_i32 s37, s39, 0
	s_lshl_b32 s38, s37, 13
	s_add_u32 s40, s44, s38
	s_addc_u32 s41, s45, 0
	global_store_dwordx2 v6, v[120:121], s[40:41] nt
	global_store_dwordx2 v6, v[122:123], s[40:41] offset:512 nt
	global_store_dwordx2 v6, v[124:125], s[40:41] offset:1024 nt
	global_store_dwordx2 v6, v[126:127], s[40:41] offset:1536 nt
	v_lshlrev_b32_e32 v8, 16, v24
	v_and_b32_e32 v9, 0xffff0000, v24
	v_lshlrev_b32_e32 v10, 16, v25
	v_and_b32_e32 v11, 0xffff0000, v25
	v_lshlrev_b32_e32 v12, 16, v26
	v_and_b32_e32 v13, 0xffff0000, v26
	v_lshlrev_b32_e32 v14, 16, v27
	v_and_b32_e32 v15, 0xffff0000, v27
	v_lshlrev_b32_e32 v16, 16, v28
	v_and_b32_e32 v17, 0xffff0000, v28
	v_lshlrev_b32_e32 v18, 16, v29
	v_and_b32_e32 v19, 0xffff0000, v29
	v_lshlrev_b32_e32 v20, 16, v30
	v_and_b32_e32 v21, 0xffff0000, v30
	v_lshlrev_b32_e32 v22, 16, v31
	v_and_b32_e32 v23, 0xffff0000, v31
	s_waitcnt vmcnt(52)
	v_mfma_f32_16x16x32_bf16 v[8:11], v[56:59], v[120:123], v[8:11]
	v_mfma_f32_16x16x32_bf16 v[12:15], v[64:67], v[120:123], v[12:15]
	v_mfma_f32_16x16x32_bf16 v[16:19], v[72:75], v[120:123], v[16:19]
	v_mfma_f32_16x16x32_bf16 v[20:23], v[80:83], v[120:123], v[20:23]
	v_mfma_f32_16x16x32_bf16 v[8:11], v[60:63], v[124:127], v[8:11]
	v_mfma_f32_16x16x32_bf16 v[12:15], v[68:71], v[124:127], v[12:15]
	v_mfma_f32_16x16x32_bf16 v[16:19], v[76:79], v[124:127], v[16:19]
	v_mfma_f32_16x16x32_bf16 v[20:23], v[84:87], v[124:127], v[20:23]
	s_add_i32 s37, s39, 4
	s_min_u32 s37, s37, 0x7f
	s_lshl_b32 s38, s37, 13
	s_add_u32 s82, s44, s38
	s_addc_u32 s83, s45, 0
	global_load_dwordx2 v[24:25], v6, s[82:83]
	global_load_dwordx2 v[26:27], v6, s[82:83] offset:512
	global_load_dwordx2 v[28:29], v6, s[82:83] offset:1024
	global_load_dwordx2 v[30:31], v6, s[82:83] offset:1536
	s_add_u32 s82, s46, s38
	s_addc_u32 s83, s47, 0
	global_load_dwordx4 v[56:59], v7, s[82:83]
	global_load_dwordx4 v[60:63], v7, s[82:83] offset:1024
	global_load_dwordx4 v[64:67], v7, s[82:83] offset:2048
	global_load_dwordx4 v[68:71], v7, s[82:83] offset:3072
	global_load_dwordx4 v[72:75], v129, s[82:83]
	global_load_dwordx4 v[76:79], v129, s[82:83] offset:1024
	global_load_dwordx4 v[80:83], v129, s[82:83] offset:2048
	global_load_dwordx4 v[84:87], v129, s[82:83] offset:3072
	s_waitcnt vmcnt(56)
	v_cvt_pk_bf16_f32 v120, v8, v9
	v_cvt_pk_bf16_f32 v121, v10, v11
	v_cvt_pk_bf16_f32 v122, v12, v13
	v_cvt_pk_bf16_f32 v123, v14, v15
	v_cvt_pk_bf16_f32 v124, v16, v17
	v_cvt_pk_bf16_f32 v125, v18, v19
	v_cvt_pk_bf16_f32 v126, v20, v21
	v_cvt_pk_bf16_f32 v127, v22, v23
	s_add_i32 s37, s39, 1
	s_lshl_b32 s38, s37, 13
	s_add_u32 s40, s44, s38
	s_addc_u32 s41, s45, 0
	global_store_dwordx2 v6, v[120:121], s[40:41] nt
	global_store_dwordx2 v6, v[122:123], s[40:41] offset:512 nt
	global_store_dwordx2 v6, v[124:125], s[40:41] offset:1024 nt
	global_store_dwordx2 v6, v[126:127], s[40:41] offset:1536 nt
	v_lshlrev_b32_e32 v8, 16, v32
	v_and_b32_e32 v9, 0xffff0000, v32
	v_lshlrev_b32_e32 v10, 16, v33
	v_and_b32_e32 v11, 0xffff0000, v33
	v_lshlrev_b32_e32 v12, 16, v34
	v_and_b32_e32 v13, 0xffff0000, v34
	v_lshlrev_b32_e32 v14, 16, v35
	v_and_b32_e32 v15, 0xffff0000, v35
	v_lshlrev_b32_e32 v16, 16, v36
	v_and_b32_e32 v17, 0xffff0000, v36
	v_lshlrev_b32_e32 v18, 16, v37
	v_and_b32_e32 v19, 0xffff0000, v37
	v_lshlrev_b32_e32 v20, 16, v38
	v_and_b32_e32 v21, 0xffff0000, v38
	v_lshlrev_b32_e32 v22, 16, v39
	v_and_b32_e32 v23, 0xffff0000, v39
	s_waitcnt vmcnt(52)
; __device__ __forceinline__ float bf_lo(unsigned u) { return __uint_as_float(u << 16); }
; __device__ __forceinline__ float bf_hi(unsigned u) { return __uint_as_float(u & 0xffff0000u); }
; __device__ __forceinline__ unsigned pk2(float lo, float hi) { return pg8::cvt_pk_bf16(lo, hi); }
; __device__ __forceinline__ void scan_phase(const Ctx& X, int wave, int lane) {
;     ...
;         SCAN_LOAD_G(0, 0) SCAN_LOAD_G(1, 1) SCAN_LOAD_G(2, 2)
; #pragma unroll 1
;         for (int c0 = 0; c0 < NCH; c0 += 4) {
; #pragma unroll
;             for (int k = 0; k < 4; ++k) {
;                 const int c = c0 + k;
;                 SCAN_LOAD_G((k + 3) & 3, c + 3)
;                 bf16_t* bcc = bc0 + (size_t)c * 4096;
;                 u32x2 sp[4];
; #pragma unroll
;                 for (int t = 0; t < 4; ++t) { sp[t].x = pk2(S[t][0], S[t][1]); sp[t].y = pk2(S[t][2], S[t][3]);
;                     asm volatile("" : "+v"(sp[t].x) : "v"(cb[k][t].x));
;                     *(u32x2*)(bcc + 256 * t) = sp[t]; }
;                 bf16x8 bfr[2];
; #pragma unroll
;                 for (int s2 = 0; s2 < 2; ++s2) { u32x4 w; w.x = sp[2 * s2].x; w.y = sp[2 * s2].y; w.z = sp[2 * s2 + 1].x; w.w = sp[2 * s2 + 1].y; bfr[s2] = __builtin_bit_cast(bf16x8, w); }
; #pragma unroll
;                 for (int t = 0; t < 4; ++t) {
;                     f32x4 acc = (f32x4){bf_lo(cb[k][t].x), bf_hi(cb[k][t].x), bf_lo(cb[k][t].y), bf_hi(cb[k][t].y)};
; #pragma unroll
;                     for (int s2 = 0; s2 < 2; ++s2) { u32x4 w; w.x = ca[k][t][s2][0].x; w.y = ca[k][t][s2][0].y; w.z = ca[k][t][s2][1].x; w.w = ca[k][t][s2][1].y;
;                         acc = __builtin_amdgcn_mfma_f32_16x16x32_bf16(__builtin_bit_cast(bf16x8, w), bfr[s2], acc, 0, 0, 0); }
;                     S[t][0] = acc[0]; S[t][1] = acc[1]; S[t][2] = acc[2]; S[t][3] = acc[3];
;                 }
;             }
;         }
	v_mfma_f32_16x16x32_bf16 v[8:11], v[88:91], v[120:123], v[8:11]
	v_mfma_f32_16x16x32_bf16 v[12:15], v[96:99], v[120:123], v[12:15]
	v_mfma_f32_16x16x32_bf16 v[16:19], v[104:107], v[120:123], v[16:19]
	v_mfma_f32_16x16x32_bf16 v[20:23], v[112:115], v[120:123], v[20:23]
	v_mfma_f32_16x16x32_bf16 v[8:11], v[92:95], v[124:127], v[8:11]
	v_mfma_f32_16x16x32_bf16 v[12:15], v[100:103], v[124:127], v[12:15]
	v_mfma_f32_16x16x32_bf16 v[16:19], v[108:111], v[124:127], v[16:19]
	v_mfma_f32_16x16x32_bf16 v[20:23], v[116:119], v[124:127], v[20:23]
	s_add_i32 s37, s39, 5
	s_min_u32 s37, s37, 0x7f
	s_lshl_b32 s38, s37, 13
	s_add_u32 s82, s44, s38
	s_addc_u32 s83, s45, 0
	global_load_dwordx2 v[32:33], v6, s[82:83]
	global_load_dwordx2 v[34:35], v6, s[82:83] offset:512
	global_load_dwordx2 v[36:37], v6, s[82:83] offset:1024
	global_load_dwordx2 v[38:39], v6, s[82:83] offset:1536
	s_add_u32 s82, s46, s38
	s_addc_u32 s83, s47, 0
	global_load_dwordx4 v[88:91], v7, s[82:83]
	global_load_dwordx4 v[92:95], v7, s[82:83] offset:1024
	global_load_dwordx4 v[96:99], v7, s[82:83] offset:2048
	global_load_dwordx4 v[100:103], v7, s[82:83] offset:3072
	global_load_dwordx4 v[104:107], v129, s[82:83]
	global_load_dwordx4 v[108:111], v129, s[82:83] offset:1024
	global_load_dwordx4 v[112:115], v129, s[82:83] offset:2048
	global_load_dwordx4 v[116:119], v129, s[82:83] offset:3072
	s_waitcnt vmcnt(56)
	v_cvt_pk_bf16_f32 v120, v8, v9
	v_cvt_pk_bf16_f32 v121, v10, v11
	v_cvt_pk_bf16_f32 v122, v12, v13
	v_cvt_pk_bf16_f32 v123, v14, v15
	v_cvt_pk_bf16_f32 v124, v16, v17
	v_cvt_pk_bf16_f32 v125, v18, v19
	v_cvt_pk_bf16_f32 v126, v20, v21
	v_cvt_pk_bf16_f32 v127, v22, v23
	s_add_i32 s37, s39, 2
	s_lshl_b32 s38, s37, 13
	s_add_u32 s40, s44, s38
	s_addc_u32 s41, s45, 0
	global_store_dwordx2 v6, v[120:121], s[40:41] nt
	global_store_dwordx2 v6, v[122:123], s[40:41] offset:512 nt
	global_store_dwordx2 v6, v[124:125], s[40:41] offset:1024 nt
	global_store_dwordx2 v6, v[126:127], s[40:41] offset:1536 nt
	v_lshlrev_b32_e32 v8, 16, v40
	v_and_b32_e32 v9, 0xffff0000, v40
	v_lshlrev_b32_e32 v10, 16, v41
	v_and_b32_e32 v11, 0xffff0000, v41
	v_lshlrev_b32_e32 v12, 16, v42
	v_and_b32_e32 v13, 0xffff0000, v42
	v_lshlrev_b32_e32 v14, 16, v43
	v_and_b32_e32 v15, 0xffff0000, v43
	v_lshlrev_b32_e32 v16, 16, v44
	v_and_b32_e32 v17, 0xffff0000, v44
	v_lshlrev_b32_e32 v18, 16, v45
	v_and_b32_e32 v19, 0xffff0000, v45
	v_lshlrev_b32_e32 v20, 16, v46
	v_and_b32_e32 v21, 0xffff0000, v46
	v_lshlrev_b32_e32 v22, 16, v47
	v_and_b32_e32 v23, 0xffff0000, v47
	s_waitcnt vmcnt(52)
	v_mfma_f32_16x16x32_bf16 v[8:11], v[132:135], v[120:123], v[8:11]
	v_mfma_f32_16x16x32_bf16 v[12:15], v[140:143], v[120:123], v[12:15]
	v_mfma_f32_16x16x32_bf16 v[16:19], v[148:151], v[120:123], v[16:19]
	v_mfma_f32_16x16x32_bf16 v[20:23], v[168:171], v[120:123], v[20:23]
	v_mfma_f32_16x16x32_bf16 v[8:11], v[136:139], v[124:127], v[8:11]
	v_mfma_f32_16x16x32_bf16 v[12:15], v[144:147], v[124:127], v[12:15]
	v_mfma_f32_16x16x32_bf16 v[16:19], v[164:167], v[124:127], v[16:19]
	v_mfma_f32_16x16x32_bf16 v[20:23], v[172:175], v[124:127], v[20:23]
	s_add_i32 s37, s39, 6
	s_min_u32 s37, s37, 0x7f
	s_lshl_b32 s38, s37, 13
	s_add_u32 s82, s44, s38
	s_addc_u32 s83, s45, 0
	global_load_dwordx2 v[40:41], v6, s[82:83]
	global_load_dwordx2 v[42:43], v6, s[82:83] offset:512
	global_load_dwordx2 v[44:45], v6, s[82:83] offset:1024
	global_load_dwordx2 v[46:47], v6, s[82:83] offset:1536
	s_add_u32 s82, s46, s38
	s_addc_u32 s83, s47, 0
	global_load_dwordx4 v[132:135], v7, s[82:83]
	global_load_dwordx4 v[136:139], v7, s[82:83] offset:1024
	global_load_dwordx4 v[140:143], v7, s[82:83] offset:2048
	global_load_dwordx4 v[144:147], v7, s[82:83] offset:3072
	global_load_dwordx4 v[148:151], v129, s[82:83]
	global_load_dwordx4 v[164:167], v129, s[82:83] offset:1024
	global_load_dwordx4 v[168:171], v129, s[82:83] offset:2048
	global_load_dwordx4 v[172:175], v129, s[82:83] offset:3072
	s_waitcnt vmcnt(56)
	v_cvt_pk_bf16_f32 v120, v8, v9
	v_cvt_pk_bf16_f32 v121, v10, v11
	v_cvt_pk_bf16_f32 v122, v12, v13
	v_cvt_pk_bf16_f32 v123, v14, v15
	v_cvt_pk_bf16_f32 v124, v16, v17
	v_cvt_pk_bf16_f32 v125, v18, v19
	v_cvt_pk_bf16_f32 v126, v20, v21
	v_cvt_pk_bf16_f32 v127, v22, v23
	s_add_i32 s37, s39, 3
	s_lshl_b32 s38, s37, 13
	s_add_u32 s40, s44, s38
	s_addc_u32 s41, s45, 0
	global_store_dwordx2 v6, v[120:121], s[40:41] nt
	global_store_dwordx2 v6, v[122:123], s[40:41] offset:512 nt
	global_store_dwordx2 v6, v[124:125], s[40:41] offset:1024 nt
	global_store_dwordx2 v6, v[126:127], s[40:41] offset:1536 nt
	v_lshlrev_b32_e32 v8, 16, v48
	v_and_b32_e32 v9, 0xffff0000, v48
	v_lshlrev_b32_e32 v10, 16, v49
	v_and_b32_e32 v11, 0xffff0000, v49
	v_lshlrev_b32_e32 v12, 16, v50
	v_and_b32_e32 v13, 0xffff0000, v50
	v_lshlrev_b32_e32 v14, 16, v51
	v_and_b32_e32 v15, 0xffff0000, v51
	v_lshlrev_b32_e32 v16, 16, v52
	v_and_b32_e32 v17, 0xffff0000, v52
	v_lshlrev_b32_e32 v18, 16, v53
	v_and_b32_e32 v19, 0xffff0000, v53
	v_lshlrev_b32_e32 v20, 16, v54
	v_and_b32_e32 v21, 0xffff0000, v54
	v_lshlrev_b32_e32 v22, 16, v55
	v_and_b32_e32 v23, 0xffff0000, v55
	s_waitcnt vmcnt(52)
	v_mfma_f32_16x16x32_bf16 v[8:11], v[176:179], v[120:123], v[8:11]
	v_mfma_f32_16x16x32_bf16 v[12:15], v[188:191], v[120:123], v[12:15]
	v_mfma_f32_16x16x32_bf16 v[16:19], v[196:199], v[120:123], v[16:19]
	v_mfma_f32_16x16x32_bf16 v[20:23], v[204:207], v[120:123], v[20:23]
	v_mfma_f32_16x16x32_bf16 v[8:11], v[184:187], v[124:127], v[8:11]
	v_mfma_f32_16x16x32_bf16 v[12:15], v[192:195], v[124:127], v[12:15]
	v_mfma_f32_16x16x32_bf16 v[16:19], v[200:203], v[124:127], v[16:19]
	v_mfma_f32_16x16x32_bf16 v[20:23], v[208:211], v[124:127], v[20:23]
	s_add_i32 s39, s39, 4
	s_cmpk_lt_u32 s39, 0x80
	s_cbranch_scc1 .Lsg_loop
	s_branch .LBB0_739
